# v33: v22 + SGPR-base/32-bit-offset tile loads + tile-max chain without self-max canonicalisation (5 VALU fewer per tile)
# speedup vs baseline: 1.0180x; 1.0099x over previous
; DI float fexp2(float x) { return __builtin_amdgcn_exp2f(x); }
; DI float half_max(float v) { const auto r = __builtin_amdgcn_permlane32_swap(__float_as_uint(v), __float_as_uint(v), false, false); return fmaxf(__uint_as_float(r[0]), __uint_as_float(r[1])); }
; template <int PM> DI void attn_phase(const Params& p, int l, char* smem, int* s_item, int wv, int cidx) {
;     ...
;           float mt = sacc[0][0];
; #pragma unroll
;           for (int e = 1; e < 16; ++e) mt = fmaxf(mt, sacc[0][e]);
; #pragma unroll
;           for (int e = 0; e < 16; ++e) mt = fmaxf(mt, sacc[1][e]);
;           mt = half_max(mt);
;           if (__builtin_amdgcn_ballot_w64(mt > m + 8.f) != 0ull) {
;             const float mnew = fmaxf(m, mt);
;             const float alpha = fexp2(m - mnew);
;             m = mnew;
;             lsum *= alpha;
; #pragma unroll
;             for (int db = 0; db < 4; ++db)
; #pragma unroll
;               for (int e = 0; e < 16; ++e) Oacc[db][e] *= alpha;
;           }
.LBB0_512:
	s_waitcnt lgkmcnt(2)
	v_max_f32_e32 v0, v16, v17
	v_max3_f32 v0, v0, v18, v19
	v_max3_f32 v0, v0, v20, v21
	v_max3_f32 v0, v0, v22, v23
	v_max3_f32 v0, v0, v24, v25
	v_max3_f32 v0, v0, v26, v27
	v_max3_f32 v0, v0, v28, v29
	v_max3_f32 v0, v0, v30, v31
	v_max3_f32 v0, v0, v32, v33
	v_max3_f32 v0, v0, v34, v35
	v_max3_f32 v0, v0, v36, v37
	v_max3_f32 v0, v0, v38, v39
	v_max3_f32 v0, v0, v40, v41
	v_max3_f32 v0, v0, v42, v43
	v_max3_f32 v0, v0, v44, v45
	v_max3_f32 v0, v0, v46, v47
	v_mov_b32_e32 v2, v0
	s_nop 1
	v_permlane32_swap_b32_e32 v0, v2
	v_max_f32_e32 v0, v0, v2
	v_add_f32_e32 v2, 0x41000000, v233
	v_cmp_gt_f32_e32 vcc, v0, v2
	s_cbranch_vccz .LBB0_514
	v_max_f32_e32 v0, v0, v0
	v_max_f32_e32 v2, v233, v233
	v_max_f32_e32 v2, v2, v0
	v_sub_f32_e32 v0, v233, v2
	v_exp_f32_e32 v0, v0
	v_mov_b32_e32 v233, v2
	v_pk_mul_f32 v[142:143], v[142:143], v[0:1] op_sel_hi:[1,0]
	v_pk_mul_f32 v[140:141], v[140:141], v[0:1] op_sel_hi:[1,0]
	v_pk_mul_f32 v[138:139], v[138:139], v[0:1] op_sel_hi:[1,0]
	v_pk_mul_f32 v[136:137], v[136:137], v[0:1] op_sel_hi:[1,0]
	v_pk_mul_f32 v[134:135], v[134:135], v[0:1] op_sel_hi:[1,0]
	v_pk_mul_f32 v[132:133], v[132:133], v[0:1] op_sel_hi:[1,0]
	v_pk_mul_f32 v[130:131], v[130:131], v[0:1] op_sel_hi:[1,0]
	v_pk_mul_f32 v[128:129], v[128:129], v[0:1] op_sel_hi:[1,0]
	v_pk_mul_f32 v[126:127], v[126:127], v[0:1] op_sel_hi:[1,0]
	v_pk_mul_f32 v[124:125], v[124:125], v[0:1] op_sel_hi:[1,0]
	v_pk_mul_f32 v[122:123], v[122:123], v[0:1] op_sel_hi:[1,0]
	v_pk_mul_f32 v[120:121], v[120:121], v[0:1] op_sel_hi:[1,0]
	v_pk_mul_f32 v[118:119], v[118:119], v[0:1] op_sel_hi:[1,0]
	v_pk_mul_f32 v[116:117], v[116:117], v[0:1] op_sel_hi:[1,0]
	v_pk_mul_f32 v[114:115], v[114:115], v[0:1] op_sel_hi:[1,0]
	v_pk_mul_f32 v[112:113], v[112:113], v[0:1] op_sel_hi:[1,0]
	v_pk_mul_f32 v[110:111], v[110:111], v[0:1] op_sel_hi:[1,0]
	v_pk_mul_f32 v[108:109], v[108:109], v[0:1] op_sel_hi:[1,0]
	v_pk_mul_f32 v[106:107], v[106:107], v[0:1] op_sel_hi:[1,0]
	v_pk_mul_f32 v[104:105], v[104:105], v[0:1] op_sel_hi:[1,0]
	v_pk_mul_f32 v[102:103], v[102:103], v[0:1] op_sel_hi:[1,0]
	v_pk_mul_f32 v[100:101], v[100:101], v[0:1] op_sel_hi:[1,0]
	v_pk_mul_f32 v[98:99], v[98:99], v[0:1] op_sel_hi:[1,0]
	v_pk_mul_f32 v[96:97], v[96:97], v[0:1] op_sel_hi:[1,0]
	v_pk_mul_f32 v[94:95], v[94:95], v[0:1] op_sel_hi:[1,0]
	v_pk_mul_f32 v[92:93], v[92:93], v[0:1] op_sel_hi:[1,0]
	v_pk_mul_f32 v[90:91], v[90:91], v[0:1] op_sel_hi:[1,0]
	v_pk_mul_f32 v[88:89], v[88:89], v[0:1] op_sel_hi:[1,0]
	v_pk_mul_f32 v[86:87], v[86:87], v[0:1] op_sel_hi:[1,0]
	v_pk_mul_f32 v[84:85], v[84:85], v[0:1] op_sel_hi:[1,0]
	v_pk_mul_f32 v[82:83], v[82:83], v[0:1] op_sel_hi:[1,0]
	v_pk_mul_f32 v[80:81], v[80:81], v[0:1] op_sel_hi:[1,0]
	v_mul_f32_e32 v235, v235, v0
